# B1 queue order: lru pass 0 / pool / kmax items first, select items last in longest-first order
# baseline (speedup 1.0000x reference)
; DI int pop_block(int* ctr, int*) {
;   __syncthreads();
;   if (threadIdx.x == 0) sh_item = atomicAdd(ctr, 1);
;   __syncthreads();
;   return __builtin_amdgcn_readfirstlane(sh_item);
; }
; DI void phase_b1(const Params& p, int layer, char*, int*) {
;   int* ctr = (int*)(p.ws + W_CTR) + layer * 4 + 0;
;   for (;;) {
;     int it = pop_block(ctr, nullptr);
;     if (it >= N_SEL + N_LRU1 + N_POOL + N_KMAX) break;
;     if (it >= N_SEL + N_LRU1 + N_POOL) { int j = it - (N_SEL + N_LRU1 + N_POOL); kmax_item(p, j >> 3, j & 7, smem); }
;     else if (it < N_SEL) {
;       if (it < 1024) { int c = 64 - (it >> 4), b = (it & 15) >> 2, sub = it & 3; select_item(p, 1, b, c, sub, smem); }
;       else if (it < 1088) { int j = it - 1024; select_item(p, 0, j >> 2, 0, j & 3, smem); }
;       else select_item(p, 1, it - 1088, 0, 0, smem);
;     } else if (it < N_SEL + N_LRU1) {
;       int j = it - N_SEL;
;       int sq = j / (NTILE_P * 8), rem = j % (NTILE_P * 8);
;       lru_tile(p, layer, 1, sq, rem >> 3, rem & 7, 0, smem);
;     } else {
;       int j = it - N_SEL - N_LRU1;
;       if (j < NB_P * NTILE_P * 4) { int sq = j / (NTILE_P * 4), rem = j % (NTILE_P * 4); pool_item(p, layer, 1, sq, rem >> 2, rem & 3, smem); }
;       else { j -= NB_P * NTILE_P * 4; pool_item(p, layer, 0, j >> 2, 0, j & 3, smem); }
;     }
;   }
.LBB0_1993:
	s_barrier
	s_and_saveexec_b64 s[0:1], s[96:97]
	s_cbranch_execz .LBB0_1997
	v_mov_b32_e32 v1, 1
	v_readlane_b32 s4, v251, 47
	v_readlane_b32 s5, v251, 48
	s_nop 4
	global_atomic_add v1, v129, v1, s[4:5] sc0
	s_waitcnt vmcnt(0)
	v_subrev_u32_e32 v0, 0xd10, v1
	v_add_u32_e32 v2, 0x210, v0
	v_subrev_u32_e32 v3, 64, v0
	v_cmp_gt_u32_e32 vcc, 0x230, v0
	s_nop 1
	v_cndmask_b32_e32 v2, v3, v2, vcc
	v_cmp_gt_u32_e32 vcc, 0x1f0, v0
	s_nop 1
	v_cndmask_b32_e32 v2, v2, v0, vcc
	v_cmp_gt_u32_e32 vcc, 0x440, v0
	s_nop 1
	v_cndmask_b32_e32 v2, v0, v2, vcc
	v_add_u32_e32 v3, 0x444, v1
	v_cmp_gt_u32_e32 vcc, 0xd10, v1
	s_nop 1
	v_cndmask_b32_e32 v2, v2, v3, vcc
	v_cmp_gt_u32_e32 vcc, 0x1154, v1
	s_nop 1
	v_cndmask_b32_e32 v1, v1, v2, vcc
	ds_write_b32 v129, v1 offset:32
